# P1: second memory K|V projection GEMM moved to workgroups that own only two input-projection tiles (critical path 4 -> 3 tile times)
# baseline (speedup 1.0000x reference)
; #define PG8_BAR __builtin_amdgcn_s_barrier()
; template <class Epi, class Sched, bool ALIGN_EPI = false, bool SP2 = false>
; __device__ __forceinline__ void gemm_phase(PG8_LAS unsigned char* lds, const Gemm g, const Sched& S, const Epi& E) {
;     int tid_o = threadIdx.x; asm volatile("" : "+v"(tid_o)); const int tid = tid_o, wid = __builtin_amdgcn_readfirstlane(tid >> 6), lane = tid & 63, wr = wid >> 2, wc = wid & 3, fr = lane & 15, fq = lane >> 4;
;     const int K = g.K, nt = K / BK;
;     unsigned voffA[2], voffB[2];
; #pragma unroll
;     for (int i = 0; i < 2; ++i) { int R, C; stage_rc(tid * 16 + i * 8192, R, C); const int Rb = Epi::PERM ? ((R & ~31) + perm32(R & 31)) : R;
;         voffA[i] = (unsigned)(R * K + C) * 2u; voffB[i] = (unsigned)(Rb * K + C) * 2u; }
;     const size_t kstep = (size_t)(BK * 2);
;     const size_t hstep = (size_t)HALF * K * 2;
;     const size_t tstep = 2 * hstep;
;     const unsigned ldsw = (unsigned)wid * 1024u;
;     const int aoff = lds_byte(wr * 64 + fr, fq * 8), boff = lds_byte(wc * 32 + fr, fq * 8);
;     ...
;     Unit cur, nxt; int ui = 0;
;     if (!S.next(0, cur)) return;
;     f32x4 acc[2][2][4][2];
; #pragma unroll
;     for (int a = 0; a < 2; ++a)
; #pragma unroll
;         for (int b = 0; b < 2; ++b)
; #pragma unroll
;             for (int m = 0; m < 4; ++m)
; #pragma unroll
;                 for (int n = 0; n < 2; ++n) acc[a][b][m][n] = (f32x4){0.f, 0.f, 0.f, 0.f};
;     bf16x8 At[4][2], B0[2][2], B1[2][2];
;     const char* cA = (const char*)g.A + (size_t)cur.pm * tstep; const char* cB = (const char*)g.Bt + (size_t)cur.pn * tstep;
;     S.a_ready(cur);
;     if constexpr (SP2) {
;         PG8_STAGE(PG8_SB(0, 0), cB, voffB); PG8_STAGE(PG8_SB(0, 1), cB + hstep, voffB); PG8_STAGE(PG8_SA(0, 0), cA, voffA); PG8_STAGE(PG8_SA(0, 1), cA + hstep, voffA);
;         if (wr == 1) PG8_BAR;
;         PG8_WAIT_V(2); PG8_BAR;
;         PG8_STAGE(PG8_SB(1, 0), cB + kstep, voffB); PG8_STAGE(PG8_SA(1, 0), cA + kstep, voffA); PG8_STAGE(PG8_SB(1, 1), cB + hstep + kstep, voffB);
;         PG8_WAIT_V(6); PG8_BAR;
;     } else {
; __global__ void __launch_bounds__(NTHREADS, 2) mega_fwd(Args args) {
;     ...
;         run_gemm(lds, (const bf16*)(ws + S_MN) + (size_t)512 * 1024, (const bf16*)(ws + W_WMKV) + (size_t)1024 * 1024, 512, 1024, 1024, pg8::EpiStore{(bf16*)(ws + S_MKV) + (size_t)512 * 1024, 1024}, (bid + 192) % G);
.LBB0_189:
	s_add_i32 s2, s84, 0x78
	s_ashr_i32 s3, s2, 31
	s_abs_i32 s2, s2
	s_mul_hi_u32 s4, s2, s40
	s_mul_i32 s4, s4, s39
	s_sub_i32 s2, s2, s4
	s_sub_i32 s4, s2, s39
	s_cmp_ge_u32 s2, s39
	s_cselect_b32 s2, s4, s2
	s_sub_i32 s4, s2, s39
	s_cmp_ge_u32 s2, s39
	s_cselect_b32 s2, s4, s2
	s_xor_b32 s2, s2, s3
	s_sub_i32 s39, s2, s3
	v_mov_b32_e32 v9, v212
	s_cmp_gt_i32 s39, 7
	v_readfirstlane_b32 s3, v9
	s_cbranch_scc1 .LBB0_205
	v_lshlrev_b32_e32 v0, 4, v9
	v_add_u32_e32 v1, 0x2000, v0
	v_ashrrev_i32_e32 v2, 31, v1
	v_lshrrev_b32_e32 v2, 22, v2
	v_add_u32_e32 v2, v1, v2
	v_ashrrev_i32_e32 v8, 10, v2
	v_mul_i32_i24_e32 v3, 0x400, v8
	v_sub_u32_e32 v1, v1, v3
	v_lshrrev_b32_e32 v3, 4, v1
	v_bitop3_b32 v1, v3, v1, 32 bitop3:0x6c
	v_ashrrev_i32_e32 v3, 31, v1
	v_lshrrev_b32_e32 v3, 26, v3
	v_add_u32_e32 v3, v1, v3
	v_ashrrev_i32_e32 v10, 6, v3
	v_and_b32_e32 v3, 0xc0, v3
	v_sub_u32_e32 v1, v1, v3
	v_mov_b32_e32 v3, 1
	v_ashrrev_i16_sdwa v1, v3, sext(v1) dst_sel:DWORD dst_unused:UNUSED_PAD src0_sel:DWORD src1_sel:BYTE_0
	v_bfe_i32 v11, v1, 0, 16
	v_lshlrev_b32_e32 v1, 3, v8
	v_and_b32_e32 v1, -16, v1
	v_add_u32_e32 v1, v10, v1
	v_lshlrev_b32_e32 v2, 5, v8
	v_and_b32_e32 v4, 3, v10
	s_mov_b32 s4, 0x1fffe0
	v_lshrrev_b32_e32 v5, 2, v1
	v_lshlrev_b32_e32 v6, 1, v1
	v_and_b32_e32 v2, 32, v2
	v_and_or_b32 v4, v1, s4, v4
	v_and_b32_e32 v5, 4, v5
	v_and_b32_e32 v6, 24, v6
	v_or3_b32 v4, v4, v5, v6
	v_add_lshl_u32 v2, v2, v11, 1
	v_lshl_add_u32 v128, v4, 11, v2
	v_lshl_add_u32 v130, v1, 11, v2
	v_bfe_i32 v2, v9, 27, 1
	v_lshrrev_b32_e32 v2, 22, v2
	v_add_u32_e32 v2, v0, v2
	v_and_b32_e32 v2, 0xfffffc00, v2
	v_sub_u32_e32 v0, v0, v2
	v_lshrrev_b32_e32 v2, 4, v0
	v_bitop3_b32 v0, v2, v0, 32 bitop3:0x6c
	s_load_dwordx4 s[8:11], s[82:83], 0x100
	v_ashrrev_i32_e32 v2, 31, v0
	v_lshrrev_b32_e32 v2, 26, v2
	v_ashrrev_i32_e32 v1, 31, v9
	v_add_u32_e32 v2, v0, v2
	s_ashr_i32 s2, s3, 6
	v_lshrrev_b32_e32 v1, 26, v1
	v_ashrrev_i32_e32 v13, 6, v2
	v_and_b32_e32 v2, 0xc0, v2
	s_ashr_i32 s13, s3, 8
	s_lshl_b32 s40, s2, 10
	v_add_u32_e32 v1, v9, v1
	v_sub_u32_e32 v0, v0, v2
	s_waitcnt lgkmcnt(0)
	s_add_u32 s41, s10, 0x3800000
	v_ashrrev_i32_e32 v12, 6, v1
	v_ashrrev_i16_sdwa v0, v3, sext(v0) dst_sel:DWORD dst_unused:UNUSED_PAD src0_sel:DWORD src1_sel:BYTE_0
	s_addc_u32 s42, s11, 0
	v_bfe_i32 v14, v0, 0, 16
	v_lshlrev_b32_e32 v0, 3, v12
	s_add_u32 s43, s10, 0x1120000
	v_and_b32_e32 v0, -16, v0
	s_addc_u32 s44, s11, 0
	v_add_u32_e32 v0, v13, v0
	v_and_b32_e32 v2, 3, v13
	s_ashr_i32 s45, s39, 31
	v_and_or_b32 v2, v0, s4, v2
	s_lshr_b32 s4, s45, 29
	s_add_i32 s4, s39, s4
	s_ashr_i32 s5, s4, 3
	s_and_b32 s4, s4, -8
	s_sub_i32 s4, s39, s4
	s_lshr_b32 s8, s4, 31
	s_lshl_b32 s4, s4, s8
	s_add_i32 s4, s4, s5
	s_ashr_i32 s5, s4, 31
	s_lshr_b32 s5, s5, 27
	s_add_i32 s5, s4, s5
	s_ashr_i32 s8, s5, 5
	s_lshl_b32 s8, s8, 3
	v_lshlrev_b32_e32 v1, 5, v12
	v_lshrrev_b32_e32 v3, 2, v0
	v_lshlrev_b32_e32 v4, 1, v0
	s_sub_i32 s9, 2, s8
	v_and_b32_e32 v1, 32, v1
	v_and_b32_e32 v3, 4, v3
	v_and_b32_e32 v4, 24, v4
	s_min_u32 s9, s9, 8
	s_andn2_b32 s5, s5, 31
	v_or3_b32 v2, v2, v3, v4
	v_add_lshl_u32 v1, v1, v14, 1
	s_sub_i32 s10, s4, s5
	v_cvt_f32_ubyte0_e32 v3, s9
	v_lshl_add_u32 v132, v2, 11, v1
	v_cvt_f32_i32_e32 v2, s10
	v_rcp_iflag_f32_e32 v4, v3
	v_lshl_add_u32 v134, v0, 11, v1
	s_ashr_i32 s4, s10, 30
	s_or_b32 s11, s4, 1
	v_mul_f32_e32 v0, v2, v4
	v_trunc_f32_e32 v0, v0
	v_fma_f32 v1, -v0, v3, v2
	v_cvt_i32_f32_e32 v0, v0
	v_cmp_ge_f32_e64 s[4:5], |v1|, v3
	s_and_b64 s[4:5], s[4:5], exec
	s_cselect_b32 s4, s11, 0
	v_readfirstlane_b32 s5, v0
	s_add_i32 s12, s5, s4
	s_mul_i32 s4, s12, s9
	s_sub_i32 s4, s10, s4
	s_sext_i32_i8 s4, s4
	s_add_i32 s28, s8, s4
	s_ashr_i32 s29, s28, 31
	s_bfe_i64 s[8:9], s[12:13], 0x80000
	s_lshl_b64 s[4:5], s[28:29], 19
	s_lshl_b64 s[8:9], s[8:9], 19
	s_add_u32 s34, s43, s8
	s_addc_u32 s35, s44, s9
	s_add_i32 s29, s40, 0
	s_add_i32 m0, s29, 0x10000
	v_mov_b32_e32 v133, 0
	global_load_lds_dwordx4 v132, s[34:35]
	s_add_i32 m0, s29, 0x12000
	s_add_u32 s8, s34, 0x40000
	global_load_lds_dwordx4 v128, s[34:35]
	s_addc_u32 s9, s35, 0
	s_add_i32 m0, s29, 0x14000
	v_mov_b32_e32 v129, v133
	global_load_lds_dwordx4 v132, s[8:9]
	s_add_i32 m0, s29, 0x16000
	s_add_u32 s30, s41, s4
	s_addc_u32 s31, s42, s5
	s_add_i32 s33, s29, 0x2000
	global_load_lds_dwordx4 v128, s[8:9]
	s_mov_b32 m0, s29
	s_add_u32 s4, s30, 0x40000
	global_load_lds_dwordx4 v134, s[30:31]
	s_mov_b32 m0, s33
	s_addc_u32 s5, s31, 0
	s_add_i32 s46, s29, 0x4000
	global_load_lds_dwordx4 v130, s[30:31]
	s_mov_b32 m0, s46
	s_add_i32 s47, s29, 0x6000
	global_load_lds_dwordx4 v134, s[4:5]
	s_mov_b32 m0, s47
	v_mov_b32_e32 v135, v133
	global_load_lds_dwordx4 v130, s[4:5]
	v_mov_b32_e32 v131, v133
	s_cmp_eq_u32 s13, 1
	s_mov_b32 s48, 0
	v_lshl_add_u64 v[6:7], s[34:35], 0, v[132:133]
	v_lshl_add_u64 v[2:3], s[34:35], 0, v[128:129]
	v_lshl_add_u64 v[0:1], s[30:31], 0, v[134:135]
	s_cselect_b64 s[4:5], -1, 0
	s_cmp_lg_u32 s13, 1
	v_lshl_add_u64 v[4:5], s[30:31], 0, v[130:131]
	s_cbranch_scc1 .LBB0_192
	s_barrier
